# adaLN GEMV: the next item's first 32 weight rows are requested before the current item's reduction tail, so the weight stream continues across items
# baseline (speedup 1.0000x reference)
.LBB0_20:
	s_or_b64 exec, exec, s[4:5]
	s_ashr_i32 s91, s90, 31
	v_and_b32_e32 v6, 63, v4
	s_cmpk_gt_i32 s6, 0x2ff
	s_waitcnt lgkmcnt(0)
	s_barrier
	s_cbranch_scc1 .LBB0_27
	s_add_u32 s12, s2, 0x100000
	s_load_dwordx2 s[10:11], s[8:9], 0x78
	s_addc_u32 s13, s3, 0
	s_lshl_b32 s4, s20, 10
	s_add_i32 s22, s4, 0
	s_mul_i32 s4, s20, 0x300
	s_add_i32 s4, s4, 0
	v_lshlrev_b32_e32 v2, 2, v6
	s_lshl_b32 s7, s20, 8
	v_add_u32_e32 v1, s4, v2
	s_movk_i32 s4, 0xc0
	v_add_u32_e32 v5, 0, v2
	v_lshlrev_b32_e32 v7, 8, v0
	s_ashr_i32 s21, s7, 31
	v_cmp_gt_i32_e32 vcc, s4, v4
	v_mov_b32_e32 v3, 0
	s_mov_b32 s23, 0xc000
	s_mov_b32 s24, 0x18000
	s_mov_b32 s25, 0x24000
	s_mov_b32 s26, 0x30000
	s_mov_b32 s27, 0x3c000
	s_mov_b32 s28, 0x48000
	s_mov_b32 s29, 0x54000
	s_mov_b32 s30, 0x60000
	s_mov_b32 s31, 0x6c000
	s_mov_b32 s33, 0x78000
	s_mov_b32 s34, 0x84000
	s_mov_b32 s35, 0x90000
	s_mov_b32 s36, 0x9c000
	s_mov_b32 s37, 0xa8000
	s_mov_b32 s38, 0xb4000
	s_mov_b32 s39, 0xc0000
	s_mov_b32 s40, 0xcc000
	s_mov_b32 s41, 0xd8000
	s_mov_b32 s42, 0xe4000
	s_mov_b32 s43, 0xf0000
	s_mov_b32 s44, 0xfc000
	s_mov_b32 s45, 0x108000
	s_mov_b32 s46, 0x114000
	s_mov_b32 s47, 0x120000
	s_mov_b32 s48, 0x12c000
	s_mov_b32 s49, 0x138000
	s_mov_b32 s50, 0x144000
	s_mov_b32 s51, 0x150000
	s_mov_b32 s52, 0x15c000
	s_mov_b32 s53, 0x168000
	s_mov_b32 s54, 0x174000
	v_lshlrev_b32_e32 v2, 2, v6
	v_add_u32_e32 v5, v5, v7
	s_mov_b32 s55, s6
	s_mov_b32 s32, 0
	s_branch .LBB0_23

.LBB0_24:
	s_mov_b32 s17, 3
	s_cmp_lg_u32 s32, 0
	s_cbranch_scc1 .Lada_pf
	s_mov_b64 s[18:19], s[4:5]
	global_load_dword v108, v172, s[18:19] nt
	s_add_u32 s18, s18, 0xc000
	s_addc_u32 s19, s19, 0
	global_load_dword v109, v172, s[18:19] nt
	s_add_u32 s18, s18, 0xc000
	s_addc_u32 s19, s19, 0
	global_load_dword v110, v172, s[18:19] nt
	s_add_u32 s18, s18, 0xc000
	s_addc_u32 s19, s19, 0
	global_load_dword v111, v172, s[18:19] nt
	s_add_u32 s18, s18, 0xc000
	s_addc_u32 s19, s19, 0
	global_load_dword v112, v172, s[18:19] nt
	s_add_u32 s18, s18, 0xc000
	s_addc_u32 s19, s19, 0
	global_load_dword v113, v172, s[18:19] nt
	s_add_u32 s18, s18, 0xc000
	s_addc_u32 s19, s19, 0
	global_load_dword v114, v172, s[18:19] nt
	s_add_u32 s18, s18, 0xc000
	s_addc_u32 s19, s19, 0
	global_load_dword v115, v172, s[18:19] nt
	s_add_u32 s18, s18, 0xc000
	s_addc_u32 s19, s19, 0
	global_load_dword v116, v172, s[18:19] nt
	s_add_u32 s18, s18, 0xc000
	s_addc_u32 s19, s19, 0
	global_load_dword v117, v172, s[18:19] nt
	s_add_u32 s18, s18, 0xc000
	s_addc_u32 s19, s19, 0
	global_load_dword v118, v172, s[18:19] nt
	s_add_u32 s18, s18, 0xc000
	s_addc_u32 s19, s19, 0
	global_load_dword v119, v172, s[18:19] nt
	s_add_u32 s18, s18, 0xc000
	s_addc_u32 s19, s19, 0
	global_load_dword v120, v172, s[18:19] nt
	s_add_u32 s18, s18, 0xc000
	s_addc_u32 s19, s19, 0
	global_load_dword v121, v172, s[18:19] nt
	s_add_u32 s18, s18, 0xc000
	s_addc_u32 s19, s19, 0
	global_load_dword v122, v172, s[18:19] nt
	s_add_u32 s18, s18, 0xc000
	s_addc_u32 s19, s19, 0
	global_load_dword v123, v172, s[18:19] nt
	s_add_u32 s18, s18, 0xc000
	s_addc_u32 s19, s19, 0
	global_load_dword v124, v172, s[18:19] nt
	s_add_u32 s18, s18, 0xc000
	s_addc_u32 s19, s19, 0
	global_load_dword v125, v172, s[18:19] nt
	s_add_u32 s18, s18, 0xc000
	s_addc_u32 s19, s19, 0
	global_load_dword v126, v172, s[18:19] nt
	s_add_u32 s18, s18, 0xc000
	s_addc_u32 s19, s19, 0
	global_load_dword v127, v172, s[18:19] nt
	s_add_u32 s18, s18, 0xc000
	s_addc_u32 s19, s19, 0
	global_load_dword v128, v172, s[18:19] nt
	s_add_u32 s18, s18, 0xc000
	s_addc_u32 s19, s19, 0
	global_load_dword v129, v172, s[18:19] nt
	s_add_u32 s18, s18, 0xc000
	s_addc_u32 s19, s19, 0
	global_load_dword v130, v172, s[18:19] nt
	s_add_u32 s18, s18, 0xc000
	s_addc_u32 s19, s19, 0
	global_load_dword v131, v172, s[18:19] nt
	s_add_u32 s18, s18, 0xc000
	s_addc_u32 s19, s19, 0
	global_load_dword v132, v172, s[18:19] nt
	s_add_u32 s18, s18, 0xc000
	s_addc_u32 s19, s19, 0
	global_load_dword v133, v172, s[18:19] nt
	s_add_u32 s18, s18, 0xc000
	s_addc_u32 s19, s19, 0
	global_load_dword v134, v172, s[18:19] nt
	s_add_u32 s18, s18, 0xc000
	s_addc_u32 s19, s19, 0
	global_load_dword v135, v172, s[18:19] nt
	s_add_u32 s18, s18, 0xc000
	s_addc_u32 s19, s19, 0
	global_load_dword v136, v172, s[18:19] nt
	s_add_u32 s18, s18, 0xc000
	s_addc_u32 s19, s19, 0
	global_load_dword v137, v172, s[18:19] nt
	s_add_u32 s18, s18, 0xc000
	s_addc_u32 s19, s19, 0
	global_load_dword v138, v172, s[18:19] nt
	s_add_u32 s18, s18, 0xc000
	s_addc_u32 s19, s19, 0
	global_load_dword v139, v172, s[18:19] nt
	s_add_u32 s18, s18, 0xc000
	s_addc_u32 s19, s19, 0
	s_branch .Lada_loop
.Lada_pf:
	s_add_u32 s18, s4, 0x180000
	s_addc_u32 s19, s5, 0
.Lada_loop:
	global_load_dword v140, v172, s[18:19] nt
	s_add_u32 s18, s18, 0xc000
	s_addc_u32 s19, s19, 0
	global_load_dword v141, v172, s[18:19] nt
	s_add_u32 s18, s18, 0xc000
	s_addc_u32 s19, s19, 0
	global_load_dword v142, v172, s[18:19] nt
	s_add_u32 s18, s18, 0xc000
	s_addc_u32 s19, s19, 0
	global_load_dword v143, v172, s[18:19] nt
	s_add_u32 s18, s18, 0xc000
	s_addc_u32 s19, s19, 0
	global_load_dword v144, v172, s[18:19] nt
	s_add_u32 s18, s18, 0xc000
	s_addc_u32 s19, s19, 0
	global_load_dword v145, v172, s[18:19] nt
	s_add_u32 s18, s18, 0xc000
	s_addc_u32 s19, s19, 0
	global_load_dword v146, v172, s[18:19] nt
	s_add_u32 s18, s18, 0xc000
	s_addc_u32 s19, s19, 0
	global_load_dword v147, v172, s[18:19] nt
	s_add_u32 s18, s18, 0xc000
	s_addc_u32 s19, s19, 0
	global_load_dword v148, v172, s[18:19] nt
	s_add_u32 s18, s18, 0xc000
	s_addc_u32 s19, s19, 0
	global_load_dword v149, v172, s[18:19] nt
	s_add_u32 s18, s18, 0xc000
	s_addc_u32 s19, s19, 0
	global_load_dword v150, v172, s[18:19] nt
	s_add_u32 s18, s18, 0xc000
	s_addc_u32 s19, s19, 0
	global_load_dword v151, v172, s[18:19] nt
	s_add_u32 s18, s18, 0xc000
	s_addc_u32 s19, s19, 0
	global_load_dword v152, v172, s[18:19] nt
	s_add_u32 s18, s18, 0xc000
	s_addc_u32 s19, s19, 0
	global_load_dword v153, v172, s[18:19] nt
	s_add_u32 s18, s18, 0xc000
	s_addc_u32 s19, s19, 0
	global_load_dword v154, v172, s[18:19] nt
	s_add_u32 s18, s18, 0xc000
	s_addc_u32 s19, s19, 0
	global_load_dword v155, v172, s[18:19] nt
	s_add_u32 s18, s18, 0xc000
	s_addc_u32 s19, s19, 0
	global_load_dword v156, v172, s[18:19] nt
	s_add_u32 s18, s18, 0xc000
	s_addc_u32 s19, s19, 0
	global_load_dword v157, v172, s[18:19] nt
	s_add_u32 s18, s18, 0xc000
	s_addc_u32 s19, s19, 0
	global_load_dword v158, v172, s[18:19] nt
	s_add_u32 s18, s18, 0xc000
	s_addc_u32 s19, s19, 0
	global_load_dword v159, v172, s[18:19] nt
	s_add_u32 s18, s18, 0xc000
	s_addc_u32 s19, s19, 0
	global_load_dword v160, v172, s[18:19] nt
	s_add_u32 s18, s18, 0xc000
	s_addc_u32 s19, s19, 0
	global_load_dword v161, v172, s[18:19] nt
	s_add_u32 s18, s18, 0xc000
	s_addc_u32 s19, s19, 0
	global_load_dword v162, v172, s[18:19] nt
	s_add_u32 s18, s18, 0xc000
	s_addc_u32 s19, s19, 0
	global_load_dword v163, v172, s[18:19] nt
	s_add_u32 s18, s18, 0xc000
	s_addc_u32 s19, s19, 0
	global_load_dword v164, v172, s[18:19] nt
	s_add_u32 s18, s18, 0xc000
	s_addc_u32 s19, s19, 0
	global_load_dword v165, v172, s[18:19] nt
	s_add_u32 s18, s18, 0xc000
	s_addc_u32 s19, s19, 0
	global_load_dword v166, v172, s[18:19] nt
	s_add_u32 s18, s18, 0xc000
	s_addc_u32 s19, s19, 0
	global_load_dword v167, v172, s[18:19] nt
	s_add_u32 s18, s18, 0xc000
	s_addc_u32 s19, s19, 0
	global_load_dword v168, v172, s[18:19] nt
	s_add_u32 s18, s18, 0xc000
	s_addc_u32 s19, s19, 0
	global_load_dword v169, v172, s[18:19] nt
	s_add_u32 s18, s18, 0xc000
	s_addc_u32 s19, s19, 0
	global_load_dword v170, v172, s[18:19] nt
	s_add_u32 s18, s18, 0xc000
	s_addc_u32 s19, s19, 0
	global_load_dword v171, v172, s[18:19] nt
	s_add_u32 s18, s18, 0xc000
	s_addc_u32 s19, s19, 0
	v_mov_b32_e32 v173, s15
	ds_read_b128 v[12:15], v173 offset:0
	ds_read_b128 v[16:19], v173 offset:16
	ds_read_b128 v[20:23], v173 offset:32
	ds_read_b128 v[24:27], v173 offset:48
	ds_read_b128 v[28:31], v173 offset:64
	ds_read_b128 v[32:35], v173 offset:80
	ds_read_b128 v[36:39], v173 offset:96
	ds_read_b128 v[40:43], v173 offset:112
	ds_read_b128 v[44:47], v173 offset:8192
	ds_read_b128 v[48:51], v173 offset:8208
	ds_read_b128 v[52:55], v173 offset:8224
	ds_read_b128 v[56:59], v173 offset:8240
	ds_read_b128 v[60:63], v173 offset:8256
	ds_read_b128 v[64:67], v173 offset:8272
	ds_read_b128 v[68:71], v173 offset:8288
	ds_read_b128 v[72:75], v173 offset:8304
	ds_read_b128 v[76:79], v173 offset:16384
	ds_read_b128 v[80:83], v173 offset:16400
	ds_read_b128 v[84:87], v173 offset:16416
	ds_read_b128 v[88:91], v173 offset:16432
	ds_read_b128 v[92:95], v173 offset:16448
	ds_read_b128 v[96:99], v173 offset:16464
	ds_read_b128 v[100:103], v173 offset:16480
	ds_read_b128 v[104:107], v173 offset:16496
	s_addk_i32 s15, 0x80
	s_waitcnt lgkmcnt(0)
	s_waitcnt vmcnt(63)
	v_fmac_f32_e32 v10, v108, v12
	v_fmac_f32_e32 v11, v108, v44
	v_fmac_f32_e32 v7, v108, v76
	s_waitcnt vmcnt(62)
	v_fmac_f32_e32 v10, v109, v13
	v_fmac_f32_e32 v11, v109, v45
	v_fmac_f32_e32 v7, v109, v77
	s_waitcnt vmcnt(61)
	v_fmac_f32_e32 v10, v110, v14
	v_fmac_f32_e32 v11, v110, v46
	v_fmac_f32_e32 v7, v110, v78
	s_waitcnt vmcnt(60)
	v_fmac_f32_e32 v10, v111, v15
	v_fmac_f32_e32 v11, v111, v47
	v_fmac_f32_e32 v7, v111, v79
	s_waitcnt vmcnt(59)
	v_fmac_f32_e32 v10, v112, v16
	v_fmac_f32_e32 v11, v112, v48
	v_fmac_f32_e32 v7, v112, v80
	s_waitcnt vmcnt(58)
	v_fmac_f32_e32 v10, v113, v17
	v_fmac_f32_e32 v11, v113, v49
	v_fmac_f32_e32 v7, v113, v81
	s_waitcnt vmcnt(57)
	v_fmac_f32_e32 v10, v114, v18
	v_fmac_f32_e32 v11, v114, v50
	v_fmac_f32_e32 v7, v114, v82
	s_waitcnt vmcnt(56)
	v_fmac_f32_e32 v10, v115, v19
	v_fmac_f32_e32 v11, v115, v51
	v_fmac_f32_e32 v7, v115, v83
	s_waitcnt vmcnt(55)
	v_fmac_f32_e32 v10, v116, v20
	v_fmac_f32_e32 v11, v116, v52
	v_fmac_f32_e32 v7, v116, v84
	s_waitcnt vmcnt(54)
	v_fmac_f32_e32 v10, v117, v21
	v_fmac_f32_e32 v11, v117, v53
	v_fmac_f32_e32 v7, v117, v85
	s_waitcnt vmcnt(53)
	v_fmac_f32_e32 v10, v118, v22
	v_fmac_f32_e32 v11, v118, v54
	v_fmac_f32_e32 v7, v118, v86
	s_waitcnt vmcnt(52)
	v_fmac_f32_e32 v10, v119, v23
	v_fmac_f32_e32 v11, v119, v55
	v_fmac_f32_e32 v7, v119, v87
	s_waitcnt vmcnt(51)
	v_fmac_f32_e32 v10, v120, v24
	v_fmac_f32_e32 v11, v120, v56
	v_fmac_f32_e32 v7, v120, v88
	s_waitcnt vmcnt(50)
	v_fmac_f32_e32 v10, v121, v25
	v_fmac_f32_e32 v11, v121, v57
	v_fmac_f32_e32 v7, v121, v89
	s_waitcnt vmcnt(49)
	v_fmac_f32_e32 v10, v122, v26
	v_fmac_f32_e32 v11, v122, v58
	v_fmac_f32_e32 v7, v122, v90
	s_waitcnt vmcnt(48)
	v_fmac_f32_e32 v10, v123, v27
	v_fmac_f32_e32 v11, v123, v59
	v_fmac_f32_e32 v7, v123, v91
	s_waitcnt vmcnt(47)
	v_fmac_f32_e32 v10, v124, v28
	v_fmac_f32_e32 v11, v124, v60
	v_fmac_f32_e32 v7, v124, v92
	s_waitcnt vmcnt(46)
	v_fmac_f32_e32 v10, v125, v29
	v_fmac_f32_e32 v11, v125, v61
	v_fmac_f32_e32 v7, v125, v93
	s_waitcnt vmcnt(45)
	v_fmac_f32_e32 v10, v126, v30
	v_fmac_f32_e32 v11, v126, v62
	v_fmac_f32_e32 v7, v126, v94
	s_waitcnt vmcnt(44)
	v_fmac_f32_e32 v10, v127, v31
	v_fmac_f32_e32 v11, v127, v63
	v_fmac_f32_e32 v7, v127, v95
	s_waitcnt vmcnt(43)
	v_fmac_f32_e32 v10, v128, v32
	v_fmac_f32_e32 v11, v128, v64
	v_fmac_f32_e32 v7, v128, v96
	s_waitcnt vmcnt(42)
	v_fmac_f32_e32 v10, v129, v33
	v_fmac_f32_e32 v11, v129, v65
	v_fmac_f32_e32 v7, v129, v97
	s_waitcnt vmcnt(41)
	v_fmac_f32_e32 v10, v130, v34
	v_fmac_f32_e32 v11, v130, v66
	v_fmac_f32_e32 v7, v130, v98
	s_waitcnt vmcnt(40)
	v_fmac_f32_e32 v10, v131, v35
	v_fmac_f32_e32 v11, v131, v67
	v_fmac_f32_e32 v7, v131, v99
	s_waitcnt vmcnt(39)
	v_fmac_f32_e32 v10, v132, v36
	v_fmac_f32_e32 v11, v132, v68
	v_fmac_f32_e32 v7, v132, v100
	s_waitcnt vmcnt(38)
	v_fmac_f32_e32 v10, v133, v37
	v_fmac_f32_e32 v11, v133, v69
	v_fmac_f32_e32 v7, v133, v101
	s_waitcnt vmcnt(37)
	v_fmac_f32_e32 v10, v134, v38
	v_fmac_f32_e32 v11, v134, v70
	v_fmac_f32_e32 v7, v134, v102
	s_waitcnt vmcnt(36)
	v_fmac_f32_e32 v10, v135, v39
	v_fmac_f32_e32 v11, v135, v71
	v_fmac_f32_e32 v7, v135, v103
	s_waitcnt vmcnt(35)
	v_fmac_f32_e32 v10, v136, v40
	v_fmac_f32_e32 v11, v136, v72
	v_fmac_f32_e32 v7, v136, v104
	s_waitcnt vmcnt(34)
	v_fmac_f32_e32 v10, v137, v41
	v_fmac_f32_e32 v11, v137, v73
	v_fmac_f32_e32 v7, v137, v105
	s_waitcnt vmcnt(33)
	v_fmac_f32_e32 v10, v138, v42
	v_fmac_f32_e32 v11, v138, v74
	v_fmac_f32_e32 v7, v138, v106
	s_waitcnt vmcnt(32)
	v_fmac_f32_e32 v10, v139, v43
	v_fmac_f32_e32 v11, v139, v75
	v_fmac_f32_e32 v7, v139, v107
	global_load_dword v108, v172, s[18:19] nt
	s_add_u32 s18, s18, 0xc000
	s_addc_u32 s19, s19, 0
	global_load_dword v109, v172, s[18:19] nt
	s_add_u32 s18, s18, 0xc000
	s_addc_u32 s19, s19, 0
	global_load_dword v110, v172, s[18:19] nt
	s_add_u32 s18, s18, 0xc000
	s_addc_u32 s19, s19, 0
	global_load_dword v111, v172, s[18:19] nt
	s_add_u32 s18, s18, 0xc000
	s_addc_u32 s19, s19, 0
	global_load_dword v112, v172, s[18:19] nt
	s_add_u32 s18, s18, 0xc000
	s_addc_u32 s19, s19, 0
	global_load_dword v113, v172, s[18:19] nt
	s_add_u32 s18, s18, 0xc000
	s_addc_u32 s19, s19, 0
	global_load_dword v114, v172, s[18:19] nt
	s_add_u32 s18, s18, 0xc000
	s_addc_u32 s19, s19, 0
	global_load_dword v115, v172, s[18:19] nt
	s_add_u32 s18, s18, 0xc000
	s_addc_u32 s19, s19, 0
	global_load_dword v116, v172, s[18:19] nt
	s_add_u32 s18, s18, 0xc000
	s_addc_u32 s19, s19, 0
	global_load_dword v117, v172, s[18:19] nt
	s_add_u32 s18, s18, 0xc000
	s_addc_u32 s19, s19, 0
	global_load_dword v118, v172, s[18:19] nt
	s_add_u32 s18, s18, 0xc000
	s_addc_u32 s19, s19, 0
	global_load_dword v119, v172, s[18:19] nt
	s_add_u32 s18, s18, 0xc000
	s_addc_u32 s19, s19, 0
	global_load_dword v120, v172, s[18:19] nt
	s_add_u32 s18, s18, 0xc000
	s_addc_u32 s19, s19, 0
	global_load_dword v121, v172, s[18:19] nt
	s_add_u32 s18, s18, 0xc000
	s_addc_u32 s19, s19, 0
	global_load_dword v122, v172, s[18:19] nt
	s_add_u32 s18, s18, 0xc000
	s_addc_u32 s19, s19, 0
	global_load_dword v123, v172, s[18:19] nt
	s_add_u32 s18, s18, 0xc000
	s_addc_u32 s19, s19, 0
	global_load_dword v124, v172, s[18:19] nt
	s_add_u32 s18, s18, 0xc000
	s_addc_u32 s19, s19, 0
	global_load_dword v125, v172, s[18:19] nt
	s_add_u32 s18, s18, 0xc000
	s_addc_u32 s19, s19, 0
	global_load_dword v126, v172, s[18:19] nt
	s_add_u32 s18, s18, 0xc000
	s_addc_u32 s19, s19, 0
	global_load_dword v127, v172, s[18:19] nt
	s_add_u32 s18, s18, 0xc000
	s_addc_u32 s19, s19, 0
	global_load_dword v128, v172, s[18:19] nt
	s_add_u32 s18, s18, 0xc000
	s_addc_u32 s19, s19, 0
	global_load_dword v129, v172, s[18:19] nt
	s_add_u32 s18, s18, 0xc000
	s_addc_u32 s19, s19, 0
	global_load_dword v130, v172, s[18:19] nt
	s_add_u32 s18, s18, 0xc000
	s_addc_u32 s19, s19, 0
	global_load_dword v131, v172, s[18:19] nt
	s_add_u32 s18, s18, 0xc000
	s_addc_u32 s19, s19, 0
	global_load_dword v132, v172, s[18:19] nt
	s_add_u32 s18, s18, 0xc000
	s_addc_u32 s19, s19, 0
	global_load_dword v133, v172, s[18:19] nt
	s_add_u32 s18, s18, 0xc000
	s_addc_u32 s19, s19, 0
	global_load_dword v134, v172, s[18:19] nt
	s_add_u32 s18, s18, 0xc000
	s_addc_u32 s19, s19, 0
	global_load_dword v135, v172, s[18:19] nt
	s_add_u32 s18, s18, 0xc000
	s_addc_u32 s19, s19, 0
	global_load_dword v136, v172, s[18:19] nt
	s_add_u32 s18, s18, 0xc000
	s_addc_u32 s19, s19, 0
	global_load_dword v137, v172, s[18:19] nt
	s_add_u32 s18, s18, 0xc000
	s_addc_u32 s19, s19, 0
	global_load_dword v138, v172, s[18:19] nt
	s_add_u32 s18, s18, 0xc000
	s_addc_u32 s19, s19, 0
	global_load_dword v139, v172, s[18:19] nt
	s_add_u32 s18, s18, 0xc000
	s_addc_u32 s19, s19, 0
	v_mov_b32_e32 v173, s15
	ds_read_b128 v[12:15], v173 offset:0
	ds_read_b128 v[16:19], v173 offset:16
	ds_read_b128 v[20:23], v173 offset:32
	ds_read_b128 v[24:27], v173 offset:48
	ds_read_b128 v[28:31], v173 offset:64
	ds_read_b128 v[32:35], v173 offset:80
	ds_read_b128 v[36:39], v173 offset:96
	ds_read_b128 v[40:43], v173 offset:112
	ds_read_b128 v[44:47], v173 offset:8192
	ds_read_b128 v[48:51], v173 offset:8208
	ds_read_b128 v[52:55], v173 offset:8224
	ds_read_b128 v[56:59], v173 offset:8240
	ds_read_b128 v[60:63], v173 offset:8256
	ds_read_b128 v[64:67], v173 offset:8272
	ds_read_b128 v[68:71], v173 offset:8288
	ds_read_b128 v[72:75], v173 offset:8304
	ds_read_b128 v[76:79], v173 offset:16384
	ds_read_b128 v[80:83], v173 offset:16400
	ds_read_b128 v[84:87], v173 offset:16416
	ds_read_b128 v[88:91], v173 offset:16432
	ds_read_b128 v[92:95], v173 offset:16448
	ds_read_b128 v[96:99], v173 offset:16464
	ds_read_b128 v[100:103], v173 offset:16480
	ds_read_b128 v[104:107], v173 offset:16496
	s_addk_i32 s15, 0x80
	s_waitcnt lgkmcnt(0)
	s_waitcnt vmcnt(63)
	v_fmac_f32_e32 v10, v140, v12
	v_fmac_f32_e32 v11, v140, v44
	v_fmac_f32_e32 v7, v140, v76
	s_waitcnt vmcnt(62)
	v_fmac_f32_e32 v10, v141, v13
	v_fmac_f32_e32 v11, v141, v45
	v_fmac_f32_e32 v7, v141, v77
	s_waitcnt vmcnt(61)
	v_fmac_f32_e32 v10, v142, v14
	v_fmac_f32_e32 v11, v142, v46
	v_fmac_f32_e32 v7, v142, v78
	s_waitcnt vmcnt(60)
	v_fmac_f32_e32 v10, v143, v15
	v_fmac_f32_e32 v11, v143, v47
	v_fmac_f32_e32 v7, v143, v79
	s_waitcnt vmcnt(59)
	v_fmac_f32_e32 v10, v144, v16
	v_fmac_f32_e32 v11, v144, v48
	v_fmac_f32_e32 v7, v144, v80
	s_waitcnt vmcnt(58)
	v_fmac_f32_e32 v10, v145, v17
	v_fmac_f32_e32 v11, v145, v49
	v_fmac_f32_e32 v7, v145, v81
	s_waitcnt vmcnt(57)
	v_fmac_f32_e32 v10, v146, v18
	v_fmac_f32_e32 v11, v146, v50
	v_fmac_f32_e32 v7, v146, v82
	s_waitcnt vmcnt(56)
	v_fmac_f32_e32 v10, v147, v19
	v_fmac_f32_e32 v11, v147, v51
	v_fmac_f32_e32 v7, v147, v83
	s_waitcnt vmcnt(55)
	v_fmac_f32_e32 v10, v148, v20
	v_fmac_f32_e32 v11, v148, v52
	v_fmac_f32_e32 v7, v148, v84
	s_waitcnt vmcnt(54)
	v_fmac_f32_e32 v10, v149, v21
	v_fmac_f32_e32 v11, v149, v53
	v_fmac_f32_e32 v7, v149, v85
	s_waitcnt vmcnt(53)
	v_fmac_f32_e32 v10, v150, v22
	v_fmac_f32_e32 v11, v150, v54
	v_fmac_f32_e32 v7, v150, v86
	s_waitcnt vmcnt(52)
	v_fmac_f32_e32 v10, v151, v23
	v_fmac_f32_e32 v11, v151, v55
	v_fmac_f32_e32 v7, v151, v87
	s_waitcnt vmcnt(51)
	v_fmac_f32_e32 v10, v152, v24
	v_fmac_f32_e32 v11, v152, v56
	v_fmac_f32_e32 v7, v152, v88
	s_waitcnt vmcnt(50)
	v_fmac_f32_e32 v10, v153, v25
	v_fmac_f32_e32 v11, v153, v57
	v_fmac_f32_e32 v7, v153, v89
	s_waitcnt vmcnt(49)
	v_fmac_f32_e32 v10, v154, v26
	v_fmac_f32_e32 v11, v154, v58
	v_fmac_f32_e32 v7, v154, v90
	s_waitcnt vmcnt(48)
	v_fmac_f32_e32 v10, v155, v27
	v_fmac_f32_e32 v11, v155, v59
	v_fmac_f32_e32 v7, v155, v91
	s_waitcnt vmcnt(47)
	v_fmac_f32_e32 v10, v156, v28
	v_fmac_f32_e32 v11, v156, v60
	v_fmac_f32_e32 v7, v156, v92
	s_waitcnt vmcnt(46)
	v_fmac_f32_e32 v10, v157, v29
	v_fmac_f32_e32 v11, v157, v61
	v_fmac_f32_e32 v7, v157, v93
	s_waitcnt vmcnt(45)
	v_fmac_f32_e32 v10, v158, v30
	v_fmac_f32_e32 v11, v158, v62
	v_fmac_f32_e32 v7, v158, v94
	s_waitcnt vmcnt(44)
	v_fmac_f32_e32 v10, v159, v31
	v_fmac_f32_e32 v11, v159, v63
	v_fmac_f32_e32 v7, v159, v95
	s_waitcnt vmcnt(43)
	v_fmac_f32_e32 v10, v160, v32
	v_fmac_f32_e32 v11, v160, v64
	v_fmac_f32_e32 v7, v160, v96
	s_waitcnt vmcnt(42)
	v_fmac_f32_e32 v10, v161, v33
	v_fmac_f32_e32 v11, v161, v65
	v_fmac_f32_e32 v7, v161, v97
	s_waitcnt vmcnt(41)
	v_fmac_f32_e32 v10, v162, v34
	v_fmac_f32_e32 v11, v162, v66
	v_fmac_f32_e32 v7, v162, v98
	s_waitcnt vmcnt(40)
	v_fmac_f32_e32 v10, v163, v35
	v_fmac_f32_e32 v11, v163, v67
	v_fmac_f32_e32 v7, v163, v99
	s_waitcnt vmcnt(39)
	v_fmac_f32_e32 v10, v164, v36
	v_fmac_f32_e32 v11, v164, v68
	v_fmac_f32_e32 v7, v164, v100
	s_waitcnt vmcnt(38)
	v_fmac_f32_e32 v10, v165, v37
	v_fmac_f32_e32 v11, v165, v69
	v_fmac_f32_e32 v7, v165, v101
	s_waitcnt vmcnt(37)
	v_fmac_f32_e32 v10, v166, v38
	v_fmac_f32_e32 v11, v166, v70
	v_fmac_f32_e32 v7, v166, v102
	s_waitcnt vmcnt(36)
	v_fmac_f32_e32 v10, v167, v39
	v_fmac_f32_e32 v11, v167, v71
	v_fmac_f32_e32 v7, v167, v103
	s_waitcnt vmcnt(35)
	v_fmac_f32_e32 v10, v168, v40
	v_fmac_f32_e32 v11, v168, v72
	v_fmac_f32_e32 v7, v168, v104
	s_waitcnt vmcnt(34)
	v_fmac_f32_e32 v10, v169, v41
	v_fmac_f32_e32 v11, v169, v73
	v_fmac_f32_e32 v7, v169, v105
	s_waitcnt vmcnt(33)
	v_fmac_f32_e32 v10, v170, v42
	v_fmac_f32_e32 v11, v170, v74
	v_fmac_f32_e32 v7, v170, v106
	s_waitcnt vmcnt(32)
	v_fmac_f32_e32 v10, v171, v43
	v_fmac_f32_e32 v11, v171, v75
	v_fmac_f32_e32 v7, v171, v107
	s_sub_u32 s17, s17, 1
	s_cmp_lg_u32 s17, 0
	s_cbranch_scc1 .Lada_loop
	global_load_dword v140, v172, s[18:19] nt
	s_add_u32 s18, s18, 0xc000
	s_addc_u32 s19, s19, 0
	global_load_dword v141, v172, s[18:19] nt
	s_add_u32 s18, s18, 0xc000
	s_addc_u32 s19, s19, 0
	global_load_dword v142, v172, s[18:19] nt
	s_add_u32 s18, s18, 0xc000
	s_addc_u32 s19, s19, 0
	global_load_dword v143, v172, s[18:19] nt
	s_add_u32 s18, s18, 0xc000
	s_addc_u32 s19, s19, 0
	global_load_dword v144, v172, s[18:19] nt
	s_add_u32 s18, s18, 0xc000
	s_addc_u32 s19, s19, 0
	global_load_dword v145, v172, s[18:19] nt
	s_add_u32 s18, s18, 0xc000
	s_addc_u32 s19, s19, 0
	global_load_dword v146, v172, s[18:19] nt
	s_add_u32 s18, s18, 0xc000
	s_addc_u32 s19, s19, 0
	global_load_dword v147, v172, s[18:19] nt
	s_add_u32 s18, s18, 0xc000
	s_addc_u32 s19, s19, 0
	global_load_dword v148, v172, s[18:19] nt
	s_add_u32 s18, s18, 0xc000
	s_addc_u32 s19, s19, 0
	global_load_dword v149, v172, s[18:19] nt
	s_add_u32 s18, s18, 0xc000
	s_addc_u32 s19, s19, 0
	global_load_dword v150, v172, s[18:19] nt
	s_add_u32 s18, s18, 0xc000
	s_addc_u32 s19, s19, 0
	global_load_dword v151, v172, s[18:19] nt
	s_add_u32 s18, s18, 0xc000
	s_addc_u32 s19, s19, 0
	global_load_dword v152, v172, s[18:19] nt
	s_add_u32 s18, s18, 0xc000
	s_addc_u32 s19, s19, 0
	global_load_dword v153, v172, s[18:19] nt
	s_add_u32 s18, s18, 0xc000
	s_addc_u32 s19, s19, 0
	global_load_dword v154, v172, s[18:19] nt
	s_add_u32 s18, s18, 0xc000
	s_addc_u32 s19, s19, 0
	global_load_dword v155, v172, s[18:19] nt
	s_add_u32 s18, s18, 0xc000
	s_addc_u32 s19, s19, 0
	global_load_dword v156, v172, s[18:19] nt
	s_add_u32 s18, s18, 0xc000
	s_addc_u32 s19, s19, 0
	global_load_dword v157, v172, s[18:19] nt
	s_add_u32 s18, s18, 0xc000
	s_addc_u32 s19, s19, 0
	global_load_dword v158, v172, s[18:19] nt
	s_add_u32 s18, s18, 0xc000
	s_addc_u32 s19, s19, 0
	global_load_dword v159, v172, s[18:19] nt
	s_add_u32 s18, s18, 0xc000
	s_addc_u32 s19, s19, 0
	global_load_dword v160, v172, s[18:19] nt
	s_add_u32 s18, s18, 0xc000
	s_addc_u32 s19, s19, 0
	global_load_dword v161, v172, s[18:19] nt
	s_add_u32 s18, s18, 0xc000
	s_addc_u32 s19, s19, 0
	global_load_dword v162, v172, s[18:19] nt
	s_add_u32 s18, s18, 0xc000
	s_addc_u32 s19, s19, 0
	global_load_dword v163, v172, s[18:19] nt
	s_add_u32 s18, s18, 0xc000
	s_addc_u32 s19, s19, 0
	global_load_dword v164, v172, s[18:19] nt
	s_add_u32 s18, s18, 0xc000
	s_addc_u32 s19, s19, 0
	global_load_dword v165, v172, s[18:19] nt
	s_add_u32 s18, s18, 0xc000
	s_addc_u32 s19, s19, 0
	global_load_dword v166, v172, s[18:19] nt
	s_add_u32 s18, s18, 0xc000
	s_addc_u32 s19, s19, 0
	global_load_dword v167, v172, s[18:19] nt
	s_add_u32 s18, s18, 0xc000
	s_addc_u32 s19, s19, 0
	global_load_dword v168, v172, s[18:19] nt
	s_add_u32 s18, s18, 0xc000
	s_addc_u32 s19, s19, 0
	global_load_dword v169, v172, s[18:19] nt
	s_add_u32 s18, s18, 0xc000
	s_addc_u32 s19, s19, 0
	global_load_dword v170, v172, s[18:19] nt
	s_add_u32 s18, s18, 0xc000
	s_addc_u32 s19, s19, 0
	global_load_dword v171, v172, s[18:19] nt
	s_add_u32 s18, s18, 0xc000
	s_addc_u32 s19, s19, 0
	v_mov_b32_e32 v173, s15
	ds_read_b128 v[12:15], v173 offset:0
	ds_read_b128 v[16:19], v173 offset:16
	ds_read_b128 v[20:23], v173 offset:32
	ds_read_b128 v[24:27], v173 offset:48
	ds_read_b128 v[28:31], v173 offset:64
	ds_read_b128 v[32:35], v173 offset:80
	ds_read_b128 v[36:39], v173 offset:96
	ds_read_b128 v[40:43], v173 offset:112
	ds_read_b128 v[44:47], v173 offset:8192
	ds_read_b128 v[48:51], v173 offset:8208
	ds_read_b128 v[52:55], v173 offset:8224
	ds_read_b128 v[56:59], v173 offset:8240
	ds_read_b128 v[60:63], v173 offset:8256
	ds_read_b128 v[64:67], v173 offset:8272
	ds_read_b128 v[68:71], v173 offset:8288
	ds_read_b128 v[72:75], v173 offset:8304
	ds_read_b128 v[76:79], v173 offset:16384
	ds_read_b128 v[80:83], v173 offset:16400
	ds_read_b128 v[84:87], v173 offset:16416
	ds_read_b128 v[88:91], v173 offset:16432
	ds_read_b128 v[92:95], v173 offset:16448
	ds_read_b128 v[96:99], v173 offset:16464
	ds_read_b128 v[100:103], v173 offset:16480
	ds_read_b128 v[104:107], v173 offset:16496
	s_addk_i32 s15, 0x80
	s_waitcnt lgkmcnt(0)
	s_waitcnt vmcnt(63)
	v_fmac_f32_e32 v10, v108, v12
	v_fmac_f32_e32 v11, v108, v44
	v_fmac_f32_e32 v7, v108, v76
	s_waitcnt vmcnt(62)
	v_fmac_f32_e32 v10, v109, v13
	v_fmac_f32_e32 v11, v109, v45
	v_fmac_f32_e32 v7, v109, v77
	s_waitcnt vmcnt(61)
	v_fmac_f32_e32 v10, v110, v14
	v_fmac_f32_e32 v11, v110, v46
	v_fmac_f32_e32 v7, v110, v78
	s_waitcnt vmcnt(60)
	v_fmac_f32_e32 v10, v111, v15
	v_fmac_f32_e32 v11, v111, v47
	v_fmac_f32_e32 v7, v111, v79
	s_waitcnt vmcnt(59)
	v_fmac_f32_e32 v10, v112, v16
	v_fmac_f32_e32 v11, v112, v48
	v_fmac_f32_e32 v7, v112, v80
	s_waitcnt vmcnt(58)
	v_fmac_f32_e32 v10, v113, v17
	v_fmac_f32_e32 v11, v113, v49
	v_fmac_f32_e32 v7, v113, v81
	s_waitcnt vmcnt(57)
	v_fmac_f32_e32 v10, v114, v18
	v_fmac_f32_e32 v11, v114, v50
	v_fmac_f32_e32 v7, v114, v82
	s_waitcnt vmcnt(56)
	v_fmac_f32_e32 v10, v115, v19
	v_fmac_f32_e32 v11, v115, v51
	v_fmac_f32_e32 v7, v115, v83
	s_waitcnt vmcnt(55)
	v_fmac_f32_e32 v10, v116, v20
	v_fmac_f32_e32 v11, v116, v52
	v_fmac_f32_e32 v7, v116, v84
	s_waitcnt vmcnt(54)
	v_fmac_f32_e32 v10, v117, v21
	v_fmac_f32_e32 v11, v117, v53
	v_fmac_f32_e32 v7, v117, v85
	s_waitcnt vmcnt(53)
	v_fmac_f32_e32 v10, v118, v22
	v_fmac_f32_e32 v11, v118, v54
	v_fmac_f32_e32 v7, v118, v86
	s_waitcnt vmcnt(52)
	v_fmac_f32_e32 v10, v119, v23
	v_fmac_f32_e32 v11, v119, v55
	v_fmac_f32_e32 v7, v119, v87
	s_waitcnt vmcnt(51)
	v_fmac_f32_e32 v10, v120, v24
	v_fmac_f32_e32 v11, v120, v56
	v_fmac_f32_e32 v7, v120, v88
	s_waitcnt vmcnt(50)
	v_fmac_f32_e32 v10, v121, v25
	v_fmac_f32_e32 v11, v121, v57
	v_fmac_f32_e32 v7, v121, v89
	s_waitcnt vmcnt(49)
	v_fmac_f32_e32 v10, v122, v26
	v_fmac_f32_e32 v11, v122, v58
	v_fmac_f32_e32 v7, v122, v90
	s_waitcnt vmcnt(48)
	v_fmac_f32_e32 v10, v123, v27
	v_fmac_f32_e32 v11, v123, v59
	v_fmac_f32_e32 v7, v123, v91
	s_waitcnt vmcnt(47)
	v_fmac_f32_e32 v10, v124, v28
	v_fmac_f32_e32 v11, v124, v60
	v_fmac_f32_e32 v7, v124, v92
	s_waitcnt vmcnt(46)
	v_fmac_f32_e32 v10, v125, v29
	v_fmac_f32_e32 v11, v125, v61
	v_fmac_f32_e32 v7, v125, v93
	s_waitcnt vmcnt(45)
	v_fmac_f32_e32 v10, v126, v30
	v_fmac_f32_e32 v11, v126, v62
	v_fmac_f32_e32 v7, v126, v94
	s_waitcnt vmcnt(44)
	v_fmac_f32_e32 v10, v127, v31
	v_fmac_f32_e32 v11, v127, v63
	v_fmac_f32_e32 v7, v127, v95
	s_waitcnt vmcnt(43)
	v_fmac_f32_e32 v10, v128, v32
	v_fmac_f32_e32 v11, v128, v64
	v_fmac_f32_e32 v7, v128, v96
	s_waitcnt vmcnt(42)
	v_fmac_f32_e32 v10, v129, v33
	v_fmac_f32_e32 v11, v129, v65
	v_fmac_f32_e32 v7, v129, v97
	s_waitcnt vmcnt(41)
	v_fmac_f32_e32 v10, v130, v34
	v_fmac_f32_e32 v11, v130, v66
	v_fmac_f32_e32 v7, v130, v98
	s_waitcnt vmcnt(40)
	v_fmac_f32_e32 v10, v131, v35
	v_fmac_f32_e32 v11, v131, v67
	v_fmac_f32_e32 v7, v131, v99
	s_waitcnt vmcnt(39)
	v_fmac_f32_e32 v10, v132, v36
	v_fmac_f32_e32 v11, v132, v68
	v_fmac_f32_e32 v7, v132, v100
	s_waitcnt vmcnt(38)
	v_fmac_f32_e32 v10, v133, v37
	v_fmac_f32_e32 v11, v133, v69
	v_fmac_f32_e32 v7, v133, v101
	s_waitcnt vmcnt(37)
	v_fmac_f32_e32 v10, v134, v38
	v_fmac_f32_e32 v11, v134, v70
	v_fmac_f32_e32 v7, v134, v102
	s_waitcnt vmcnt(36)
	v_fmac_f32_e32 v10, v135, v39
	v_fmac_f32_e32 v11, v135, v71
	v_fmac_f32_e32 v7, v135, v103
	s_waitcnt vmcnt(35)
	v_fmac_f32_e32 v10, v136, v40
	v_fmac_f32_e32 v11, v136, v72
	v_fmac_f32_e32 v7, v136, v104
	s_waitcnt vmcnt(34)
	v_fmac_f32_e32 v10, v137, v41
	v_fmac_f32_e32 v11, v137, v73
	v_fmac_f32_e32 v7, v137, v105
	s_waitcnt vmcnt(33)
	v_fmac_f32_e32 v10, v138, v42
	v_fmac_f32_e32 v11, v138, v74
	v_fmac_f32_e32 v7, v138, v106
	s_waitcnt vmcnt(32)
	v_fmac_f32_e32 v10, v139, v43
	v_fmac_f32_e32 v11, v139, v75
	v_fmac_f32_e32 v7, v139, v107
	s_add_i32 s76, s55, s90
	s_cmpk_gt_i32 s76, 0x2ff
	s_cselect_b32 s76, s55, s76
	s_mul_hi_i32 s77, s76, 0x2aaaaaab
	s_lshr_b32 s78, s77, 31
	s_ashr_i32 s77, s77, 5
	s_add_i32 s80, s77, s78
	s_mul_i32 s77, s80, 0xc0
	s_sub_i32 s77, s76, s77
	s_ashr_i32 s81, s80, 31
	s_lshl_b32 s82, s77, 6
	s_lshl_b64 s[78:79], s[80:81], 11
	s_add_u32 s78, s78, s7
	s_addc_u32 s79, s79, s21
	s_mul_i32 s79, s79, 0xc000
	s_mul_hi_u32 s81, s78, 0xc000
	s_add_i32 s81, s81, s79
	s_mul_i32 s78, s78, 0xc000
	v_or_b32_e32 v174, s82, v6
	s_add_u32 s78, s10, s78
	s_addc_u32 s79, s11, s81
	v_lshlrev_b32_e32 v174, 2, v174
	global_load_dword v108, v174, s[78:79] nt
	s_add_u32 s78, s78, 0xc000
	s_addc_u32 s79, s79, 0
	global_load_dword v109, v174, s[78:79] nt
	s_add_u32 s78, s78, 0xc000
	s_addc_u32 s79, s79, 0
	global_load_dword v110, v174, s[78:79] nt
	s_add_u32 s78, s78, 0xc000
	s_addc_u32 s79, s79, 0
	global_load_dword v111, v174, s[78:79] nt
	s_add_u32 s78, s78, 0xc000
	s_addc_u32 s79, s79, 0
	global_load_dword v112, v174, s[78:79] nt
	s_add_u32 s78, s78, 0xc000
	s_addc_u32 s79, s79, 0
	global_load_dword v113, v174, s[78:79] nt
	s_add_u32 s78, s78, 0xc000
	s_addc_u32 s79, s79, 0
	global_load_dword v114, v174, s[78:79] nt
	s_add_u32 s78, s78, 0xc000
	s_addc_u32 s79, s79, 0
	global_load_dword v115, v174, s[78:79] nt
	s_add_u32 s78, s78, 0xc000
	s_addc_u32 s79, s79, 0
	global_load_dword v116, v174, s[78:79] nt
	s_add_u32 s78, s78, 0xc000
	s_addc_u32 s79, s79, 0
	global_load_dword v117, v174, s[78:79] nt
	s_add_u32 s78, s78, 0xc000
	s_addc_u32 s79, s79, 0
	global_load_dword v118, v174, s[78:79] nt
	s_add_u32 s78, s78, 0xc000
	s_addc_u32 s79, s79, 0
	global_load_dword v119, v174, s[78:79] nt
	s_add_u32 s78, s78, 0xc000
	s_addc_u32 s79, s79, 0
	global_load_dword v120, v174, s[78:79] nt
	s_add_u32 s78, s78, 0xc000
	s_addc_u32 s79, s79, 0
	global_load_dword v121, v174, s[78:79] nt
	s_add_u32 s78, s78, 0xc000
	s_addc_u32 s79, s79, 0
	global_load_dword v122, v174, s[78:79] nt
	s_add_u32 s78, s78, 0xc000
	s_addc_u32 s79, s79, 0
	global_load_dword v123, v174, s[78:79] nt
	s_add_u32 s78, s78, 0xc000
	s_addc_u32 s79, s79, 0
	global_load_dword v124, v174, s[78:79] nt
	s_add_u32 s78, s78, 0xc000
	s_addc_u32 s79, s79, 0
	global_load_dword v125, v174, s[78:79] nt
	s_add_u32 s78, s78, 0xc000
	s_addc_u32 s79, s79, 0
	global_load_dword v126, v174, s[78:79] nt
	s_add_u32 s78, s78, 0xc000
	s_addc_u32 s79, s79, 0
	global_load_dword v127, v174, s[78:79] nt
	s_add_u32 s78, s78, 0xc000
	s_addc_u32 s79, s79, 0
	global_load_dword v128, v174, s[78:79] nt
	s_add_u32 s78, s78, 0xc000
	s_addc_u32 s79, s79, 0
	global_load_dword v129, v174, s[78:79] nt
	s_add_u32 s78, s78, 0xc000
	s_addc_u32 s79, s79, 0
	global_load_dword v130, v174, s[78:79] nt
	s_add_u32 s78, s78, 0xc000
	s_addc_u32 s79, s79, 0
	global_load_dword v131, v174, s[78:79] nt
	s_add_u32 s78, s78, 0xc000
	s_addc_u32 s79, s79, 0
	global_load_dword v132, v174, s[78:79] nt
	s_add_u32 s78, s78, 0xc000
	s_addc_u32 s79, s79, 0
	global_load_dword v133, v174, s[78:79] nt
	s_add_u32 s78, s78, 0xc000
	s_addc_u32 s79, s79, 0
	global_load_dword v134, v174, s[78:79] nt
	s_add_u32 s78, s78, 0xc000
	s_addc_u32 s79, s79, 0
	global_load_dword v135, v174, s[78:79] nt
	s_add_u32 s78, s78, 0xc000
	s_addc_u32 s79, s79, 0
	global_load_dword v136, v174, s[78:79] nt
	s_add_u32 s78, s78, 0xc000
	s_addc_u32 s79, s79, 0
	global_load_dword v137, v174, s[78:79] nt
	s_add_u32 s78, s78, 0xc000
	s_addc_u32 s79, s79, 0
	global_load_dword v138, v174, s[78:79] nt
	s_add_u32 s78, s78, 0xc000
	s_addc_u32 s79, s79, 0
	global_load_dword v139, v174, s[78:79] nt
	s_add_u32 s78, s78, 0xc000
	s_addc_u32 s79, s79, 0
	s_mov_b32 s32, 1
	v_mov_b32_e32 v173, s15
	ds_read_b128 v[12:15], v173 offset:0
	ds_read_b128 v[16:19], v173 offset:16
	ds_read_b128 v[20:23], v173 offset:32
	ds_read_b128 v[24:27], v173 offset:48
	ds_read_b128 v[28:31], v173 offset:64
	ds_read_b128 v[32:35], v173 offset:80
	ds_read_b128 v[36:39], v173 offset:96
	ds_read_b128 v[40:43], v173 offset:112
	ds_read_b128 v[44:47], v173 offset:8192
	ds_read_b128 v[48:51], v173 offset:8208
	ds_read_b128 v[52:55], v173 offset:8224
	ds_read_b128 v[56:59], v173 offset:8240
	ds_read_b128 v[60:63], v173 offset:8256
	ds_read_b128 v[64:67], v173 offset:8272
	ds_read_b128 v[68:71], v173 offset:8288
	ds_read_b128 v[72:75], v173 offset:8304
	ds_read_b128 v[76:79], v173 offset:16384
	ds_read_b128 v[80:83], v173 offset:16400
	ds_read_b128 v[84:87], v173 offset:16416
	ds_read_b128 v[88:91], v173 offset:16432
	ds_read_b128 v[92:95], v173 offset:16448
	ds_read_b128 v[96:99], v173 offset:16464
	ds_read_b128 v[100:103], v173 offset:16480
	ds_read_b128 v[104:107], v173 offset:16496
	s_addk_i32 s15, 0x80
	s_waitcnt lgkmcnt(0)
	s_waitcnt vmcnt(63)
	v_fmac_f32_e32 v10, v140, v12
	v_fmac_f32_e32 v11, v140, v44
	v_fmac_f32_e32 v7, v140, v76
	s_waitcnt vmcnt(62)
	v_fmac_f32_e32 v10, v141, v13
	v_fmac_f32_e32 v11, v141, v45
	v_fmac_f32_e32 v7, v141, v77
	s_waitcnt vmcnt(61)
	v_fmac_f32_e32 v10, v142, v14
	v_fmac_f32_e32 v11, v142, v46
	v_fmac_f32_e32 v7, v142, v78
	s_waitcnt vmcnt(60)
	v_fmac_f32_e32 v10, v143, v15
	v_fmac_f32_e32 v11, v143, v47
	v_fmac_f32_e32 v7, v143, v79
	s_waitcnt vmcnt(59)
	v_fmac_f32_e32 v10, v144, v16
	v_fmac_f32_e32 v11, v144, v48
	v_fmac_f32_e32 v7, v144, v80
	s_waitcnt vmcnt(58)
	v_fmac_f32_e32 v10, v145, v17
	v_fmac_f32_e32 v11, v145, v49
	v_fmac_f32_e32 v7, v145, v81
	s_waitcnt vmcnt(57)
	v_fmac_f32_e32 v10, v146, v18
	v_fmac_f32_e32 v11, v146, v50
	v_fmac_f32_e32 v7, v146, v82
	s_waitcnt vmcnt(56)
	v_fmac_f32_e32 v10, v147, v19
	v_fmac_f32_e32 v11, v147, v51
	v_fmac_f32_e32 v7, v147, v83
	s_waitcnt vmcnt(55)
	v_fmac_f32_e32 v10, v148, v20
	v_fmac_f32_e32 v11, v148, v52
	v_fmac_f32_e32 v7, v148, v84
	s_waitcnt vmcnt(54)
	v_fmac_f32_e32 v10, v149, v21
	v_fmac_f32_e32 v11, v149, v53
	v_fmac_f32_e32 v7, v149, v85
	s_waitcnt vmcnt(53)
	v_fmac_f32_e32 v10, v150, v22
	v_fmac_f32_e32 v11, v150, v54
	v_fmac_f32_e32 v7, v150, v86
	s_waitcnt vmcnt(52)
	v_fmac_f32_e32 v10, v151, v23
	v_fmac_f32_e32 v11, v151, v55
	v_fmac_f32_e32 v7, v151, v87
	s_waitcnt vmcnt(51)
	v_fmac_f32_e32 v10, v152, v24
	v_fmac_f32_e32 v11, v152, v56
	v_fmac_f32_e32 v7, v152, v88
	s_waitcnt vmcnt(50)
	v_fmac_f32_e32 v10, v153, v25
	v_fmac_f32_e32 v11, v153, v57
	v_fmac_f32_e32 v7, v153, v89
	s_waitcnt vmcnt(49)
	v_fmac_f32_e32 v10, v154, v26
	v_fmac_f32_e32 v11, v154, v58
	v_fmac_f32_e32 v7, v154, v90
	s_waitcnt vmcnt(48)
	v_fmac_f32_e32 v10, v155, v27
	v_fmac_f32_e32 v11, v155, v59
	v_fmac_f32_e32 v7, v155, v91
	s_waitcnt vmcnt(47)
	v_fmac_f32_e32 v10, v156, v28
	v_fmac_f32_e32 v11, v156, v60
	v_fmac_f32_e32 v7, v156, v92
	s_waitcnt vmcnt(46)
	v_fmac_f32_e32 v10, v157, v29
	v_fmac_f32_e32 v11, v157, v61
	v_fmac_f32_e32 v7, v157, v93
	s_waitcnt vmcnt(45)
	v_fmac_f32_e32 v10, v158, v30
	v_fmac_f32_e32 v11, v158, v62
	v_fmac_f32_e32 v7, v158, v94
	s_waitcnt vmcnt(44)
	v_fmac_f32_e32 v10, v159, v31
	v_fmac_f32_e32 v11, v159, v63
	v_fmac_f32_e32 v7, v159, v95
	s_waitcnt vmcnt(43)
	v_fmac_f32_e32 v10, v160, v32
	v_fmac_f32_e32 v11, v160, v64
	v_fmac_f32_e32 v7, v160, v96
	s_waitcnt vmcnt(42)
	v_fmac_f32_e32 v10, v161, v33
	v_fmac_f32_e32 v11, v161, v65
	v_fmac_f32_e32 v7, v161, v97
	s_waitcnt vmcnt(41)
	v_fmac_f32_e32 v10, v162, v34
	v_fmac_f32_e32 v11, v162, v66
	v_fmac_f32_e32 v7, v162, v98
	s_waitcnt vmcnt(40)
	v_fmac_f32_e32 v10, v163, v35
	v_fmac_f32_e32 v11, v163, v67
	v_fmac_f32_e32 v7, v163, v99
	s_waitcnt vmcnt(39)
	v_fmac_f32_e32 v10, v164, v36
	v_fmac_f32_e32 v11, v164, v68
	v_fmac_f32_e32 v7, v164, v100
	s_waitcnt vmcnt(38)
	v_fmac_f32_e32 v10, v165, v37
	v_fmac_f32_e32 v11, v165, v69
	v_fmac_f32_e32 v7, v165, v101
	s_waitcnt vmcnt(37)
	v_fmac_f32_e32 v10, v166, v38
	v_fmac_f32_e32 v11, v166, v70
	v_fmac_f32_e32 v7, v166, v102
	s_waitcnt vmcnt(36)
	v_fmac_f32_e32 v10, v167, v39
	v_fmac_f32_e32 v11, v167, v71
	v_fmac_f32_e32 v7, v167, v103
	s_waitcnt vmcnt(35)
	v_fmac_f32_e32 v10, v168, v40
	v_fmac_f32_e32 v11, v168, v72
	v_fmac_f32_e32 v7, v168, v104
	s_waitcnt vmcnt(34)
	v_fmac_f32_e32 v10, v169, v41
	v_fmac_f32_e32 v11, v169, v73
	v_fmac_f32_e32 v7, v169, v105
	s_waitcnt vmcnt(33)
	v_fmac_f32_e32 v10, v170, v42
	v_fmac_f32_e32 v11, v170, v74
	v_fmac_f32_e32 v7, v170, v106
	s_waitcnt vmcnt(32)
	v_fmac_f32_e32 v10, v171, v43
	v_fmac_f32_e32 v11, v171, v75
	v_fmac_f32_e32 v7, v171, v107
	ds_write2st64_b32 v1, v10, v11 offset0:96 offset1:97
	ds_write_b32 v1, v7 offset:25088
	s_waitcnt lgkmcnt(0)
	s_barrier
	s_and_saveexec_b64 s[4:5], vcc
	s_cbranch_execz .LBB0_22
	s_load_dwordx2 s[18:19], s[8:9], 0x80
	s_ashr_i32 s17, s16, 31
	s_mul_i32 s56, s14, 0xc000
	s_mul_hi_i32 s15, s14, 0xc000
	v_mov_b64_e32 v[18:19], s[12:13]
	s_waitcnt lgkmcnt(0)
	s_add_u32 s18, s18, s56
	s_addc_u32 s15, s19, s15
	s_lshl_b64 s[16:17], s[16:17], 2
	s_add_u32 s18, s18, s16
	s_addc_u32 s19, s15, s17
	global_load_dword v7, v2, s[18:19]
	ds_read2st64_b32 v[8:9], v5 offset0:96 offset1:99
	ds_read2st64_b32 v[10:11], v5 offset0:102 offset1:105
	ds_read2st64_b32 v[12:13], v5 offset0:108 offset1:111
	ds_read2st64_b32 v[14:15], v5 offset0:114 offset1:117
	v_mad_u64_u32 v[16:17], s[14:15], s14, 3, v[0:1]
	v_mad_i64_i32 v[16:17], s[14:15], v16, s23, v[18:19]
	v_lshl_add_u64 v[16:17], v[16:17], 0, s[16:17]
	s_waitcnt vmcnt(0) lgkmcnt(3)
	v_add_f32_e32 v7, v7, v8
	v_add_f32_e32 v7, v7, v9
	s_waitcnt lgkmcnt(2)
	v_add_f32_e32 v7, v7, v10
	v_add_f32_e32 v7, v7, v11
	s_waitcnt lgkmcnt(1)
	v_add_f32_e32 v7, v7, v12
	v_add_f32_e32 v7, v7, v13
	s_waitcnt lgkmcnt(0)
	v_add_f32_e32 v7, v7, v14
	v_add_f32_e32 v7, v7, v15
	v_lshl_add_u64 v[8:9], v[16:17], 0, v[2:3]
	global_store_dword v[8:9], v7, off
	s_branch .LBB0_22
.LBB0_27:
	s_waitcnt vmcnt(0)
	s_ashr_i32 s7, s6, 31
	s_lshl_b64 s[4:5], s[6:7], 9
	v_ashrrev_i32_e32 v5, 31, v4
	v_lshl_add_u64 v[0:1], s[4:5], 0, v[4:5]
	s_mov_b64 s[4:5], 0x800
	s_lshl_b64 s[62:63], s[90:91], 9
	v_cmp_gt_i64_e32 vcc, s[4:5], v[0:1]
	s_and_saveexec_b64 s[4:5], vcc
	s_cbranch_execz .LBB0_34
	v_and_b32_e32 v2, 31, v4
	v_cvt_f32_ubyte0_e32 v2, v2
	v_mul_f32_e32 v2, 0xbed49a78, v2
	v_exp_f32_e32 v2, v2
	s_mov_b32 s10, 0
	s_mov_b32 s11, 0x40180000
	v_cvt_f64_f32_e32 v[2:3], v2
	v_mul_f64 v[10:11], v[2:3], -v[2:3]
	v_div_scale_f64 v[8:9], s[6:7], s[10:11], s[10:11], v[10:11]
	v_rcp_f64_e32 v[12:13], v[8:9]
	v_mul_f64 v[14:15], v[10:11], 0.5
	s_add_u32 s6, s2, 0x200000
	s_addc_u32 s7, s3, 0
	v_fma_f64 v[16:17], -v[8:9], v[12:13], 1.0
	v_fmac_f64_e32 v[12:13], v[12:13], v[16:17]
	v_fma_f64 v[16:17], -v[8:9], v[12:13], 1.0
	v_fmac_f64_e32 v[12:13], v[12:13], v[16:17]
	v_div_scale_f64 v[16:17], vcc, v[10:11], s[10:11], v[10:11]
	v_mul_f64 v[18:19], v[16:17], v[12:13]
	v_fma_f64 v[8:9], -v[8:9], v[18:19], v[16:17]
	s_nop 1
	v_div_fmas_f64 v[8:9], v[8:9], v[12:13], v[18:19]
	v_div_fixup_f64 v[12:13], v[8:9], s[10:11], v[10:11]
	s_mov_b32 s10, 0
	s_mov_b32 s11, 0x40280000
	v_div_scale_f64 v[16:17], s[12:13], s[10:11], s[10:11], v[10:11]
	v_rcp_f64_e32 v[18:19], v[16:17]
	v_mul_f64 v[20:21], v[12:13], v[2:3]
	v_fmac_f64_e32 v[2:3], v[12:13], v[2:3]
	s_mov_b32 s12, 0
	v_fma_f64 v[12:13], -v[16:17], v[18:19], 1.0
	v_fmac_f64_e32 v[18:19], v[18:19], v[12:13]
	v_fma_f64 v[12:13], -v[16:17], v[18:19], 1.0
	v_fmac_f64_e32 v[18:19], v[18:19], v[12:13]
	v_div_scale_f64 v[12:13], vcc, v[10:11], s[10:11], v[10:11]
	v_mul_f64 v[22:23], v[12:13], v[18:19]
	s_mov_b32 s13, 0x40340000
	v_fma_f64 v[12:13], -v[16:17], v[22:23], v[12:13]
	v_div_scale_f64 v[16:17], s[14:15], s[12:13], s[12:13], v[10:11]
	v_rcp_f64_e32 v[24:25], v[16:17]
	v_div_fmas_f64 v[12:13], v[12:13], v[18:19], v[22:23]
	v_div_fixup_f64 v[12:13], v[12:13], s[10:11], v[10:11]
	s_mov_b32 s10, 0
	v_fma_f64 v[22:23], -v[16:17], v[24:25], 1.0
	v_fmac_f64_e32 v[24:25], v[24:25], v[22:23]
	v_fma_f64 v[22:23], -v[16:17], v[24:25], 1.0
	v_fmac_f64_e32 v[24:25], v[24:25], v[22:23]
	v_div_scale_f64 v[22:23], vcc, v[10:11], s[12:13], v[10:11]
	v_mul_f64 v[26:27], v[22:23], v[24:25]
	v_fma_f64 v[16:17], -v[16:17], v[26:27], v[22:23]
	s_mov_b32 s11, 0x403e0000
	s_nop 0
	v_div_fmas_f64 v[16:17], v[16:17], v[24:25], v[26:27]
	v_div_fixup_f64 v[16:17], v[16:17], s[12:13], v[10:11]
	v_div_scale_f64 v[22:23], s[12:13], s[10:11], s[10:11], v[10:11]
	v_rcp_f64_e32 v[24:25], v[22:23]
	s_mov_b32 s12, 0
	v_fma_f64 v[8:9], v[10:11], 0.5, 1.0
	s_mov_b32 s13, 0x40450000
	v_mul_f64 v[18:19], v[14:15], v[12:13]
	v_mul_f64 v[26:27], v[16:17], v[20:21]
	v_fmac_f64_e32 v[8:9], v[14:15], v[12:13]
	v_fmac_f64_e32 v[2:3], v[16:17], v[20:21]
	v_fma_f64 v[12:13], -v[22:23], v[24:25], 1.0
	v_div_scale_f64 v[16:17], s[14:15], s[12:13], s[12:13], v[10:11]
	v_fmac_f64_e32 v[24:25], v[24:25], v[12:13]
	v_rcp_f64_e32 v[20:21], v[16:17]
	v_fma_f64 v[12:13], -v[22:23], v[24:25], 1.0
	v_fmac_f64_e32 v[24:25], v[24:25], v[12:13]
	v_div_scale_f64 v[12:13], vcc, v[10:11], s[10:11], v[10:11]
	v_mul_f64 v[14:15], v[12:13], v[24:25]
	v_fma_f64 v[12:13], -v[22:23], v[14:15], v[12:13]
	v_fma_f64 v[22:23], -v[16:17], v[20:21], 1.0
	v_fmac_f64_e32 v[20:21], v[20:21], v[22:23]
	v_fma_f64 v[22:23], -v[16:17], v[20:21], 1.0
	v_div_fmas_f64 v[12:13], v[12:13], v[24:25], v[14:15]
	v_fmac_f64_e32 v[20:21], v[20:21], v[22:23]
	v_div_scale_f64 v[22:23], vcc, v[10:11], s[12:13], v[10:11]
	v_mul_f64 v[24:25], v[22:23], v[20:21]
	v_div_fixup_f64 v[12:13], v[12:13], s[10:11], v[10:11]
	v_fma_f64 v[16:17], -v[16:17], v[24:25], v[22:23]
	s_mov_b32 s10, 0
	v_div_fmas_f64 v[16:17], v[16:17], v[20:21], v[24:25]
	s_mov_b32 s11, 0x404c0000
	v_div_fixup_f64 v[16:17], v[16:17], s[12:13], v[10:11]
	v_div_scale_f64 v[20:21], s[12:13], s[10:11], s[10:11], v[10:11]
	v_rcp_f64_e32 v[22:23], v[20:21]
	v_mul_f64 v[14:15], v[12:13], v[18:19]
	v_fmac_f64_e32 v[8:9], v[12:13], v[18:19]
	s_mov_b32 s12, 0
	v_fma_f64 v[12:13], -v[20:21], v[22:23], 1.0
	v_fmac_f64_e32 v[22:23], v[22:23], v[12:13]
	v_fma_f64 v[12:13], -v[20:21], v[22:23], 1.0
	v_fmac_f64_e32 v[22:23], v[22:23], v[12:13]
	v_div_scale_f64 v[12:13], vcc, v[10:11], s[10:11], v[10:11]
	s_mov_b32 s13, 0x40520000
	v_mul_f64 v[24:25], v[16:17], v[26:27]
	v_fmac_f64_e32 v[2:3], v[16:17], v[26:27]
	v_mul_f64 v[16:17], v[12:13], v[22:23]
	v_div_scale_f64 v[18:19], s[14:15], s[12:13], s[12:13], v[10:11]
	v_fma_f64 v[12:13], -v[20:21], v[16:17], v[12:13]
	v_rcp_f64_e32 v[20:21], v[18:19]
	v_div_fmas_f64 v[12:13], v[12:13], v[22:23], v[16:17]
	v_div_fixup_f64 v[12:13], v[12:13], s[10:11], v[10:11]
	s_mov_b32 s10, 0
	v_fma_f64 v[22:23], -v[18:19], v[20:21], 1.0
	v_fmac_f64_e32 v[20:21], v[20:21], v[22:23]
	v_fma_f64 v[22:23], -v[18:19], v[20:21], 1.0
	v_fmac_f64_e32 v[20:21], v[20:21], v[22:23]
	v_div_scale_f64 v[22:23], vcc, v[10:11], s[12:13], v[10:11]
	v_mul_f64 v[26:27], v[22:23], v[20:21]
	v_fma_f64 v[18:19], -v[18:19], v[26:27], v[22:23]
	s_mov_b32 s11, 0x40568000
	s_nop 0
	v_div_fmas_f64 v[18:19], v[18:19], v[20:21], v[26:27]
	v_div_fixup_f64 v[18:19], v[18:19], s[12:13], v[10:11]
	v_div_scale_f64 v[20:21], s[12:13], s[10:11], s[10:11], v[10:11]
	v_rcp_f64_e32 v[22:23], v[20:21]
	v_mul_f64 v[16:17], v[12:13], v[14:15]
	v_fmac_f64_e32 v[8:9], v[12:13], v[14:15]
	s_mov_b32 s12, 0
	v_fma_f64 v[12:13], -v[20:21], v[22:23], 1.0
	v_fmac_f64_e32 v[22:23], v[22:23], v[12:13]
	v_fma_f64 v[12:13], -v[20:21], v[22:23], 1.0
	v_fmac_f64_e32 v[22:23], v[22:23], v[12:13]
	v_div_scale_f64 v[12:13], vcc, v[10:11], s[10:11], v[10:11]
	s_mov_b32 s13, 0x405b8000
	v_mul_f64 v[26:27], v[18:19], v[24:25]
	v_fmac_f64_e32 v[2:3], v[18:19], v[24:25]
	v_mul_f64 v[14:15], v[12:13], v[22:23]
	v_div_scale_f64 v[18:19], s[14:15], s[12:13], s[12:13], v[10:11]
	v_fma_f64 v[12:13], -v[20:21], v[14:15], v[12:13]
	v_rcp_f64_e32 v[20:21], v[18:19]
	v_div_fmas_f64 v[12:13], v[12:13], v[22:23], v[14:15]
	v_div_fixup_f64 v[12:13], v[12:13], s[10:11], v[10:11]
	s_mov_b32 s10, 0
	v_fma_f64 v[22:23], -v[18:19], v[20:21], 1.0
	v_fmac_f64_e32 v[20:21], v[20:21], v[22:23]
	v_fma_f64 v[22:23], -v[18:19], v[20:21], 1.0
	v_fmac_f64_e32 v[20:21], v[20:21], v[22:23]
	v_div_scale_f64 v[22:23], vcc, v[10:11], s[12:13], v[10:11]
	v_mul_f64 v[24:25], v[22:23], v[20:21]
	v_fma_f64 v[18:19], -v[18:19], v[24:25], v[22:23]
	s_mov_b32 s11, 0x40608000
	s_nop 0
	v_div_fmas_f64 v[18:19], v[18:19], v[20:21], v[24:25]
	v_div_fixup_f64 v[18:19], v[18:19], s[12:13], v[10:11]
	v_div_scale_f64 v[20:21], s[12:13], s[10:11], s[10:11], v[10:11]
	v_rcp_f64_e32 v[22:23], v[20:21]
	v_mul_f64 v[14:15], v[12:13], v[16:17]
	v_fmac_f64_e32 v[8:9], v[12:13], v[16:17]
	s_mov_b32 s12, 0
	v_fma_f64 v[12:13], -v[20:21], v[22:23], 1.0
	v_fmac_f64_e32 v[22:23], v[22:23], v[12:13]
	v_fma_f64 v[12:13], -v[20:21], v[22:23], 1.0
	v_fmac_f64_e32 v[22:23], v[22:23], v[12:13]
	v_div_scale_f64 v[12:13], vcc, v[10:11], s[10:11], v[10:11]
	s_mov_b32 s13, 0x40638000
	v_mul_f64 v[24:25], v[18:19], v[26:27]
	v_fmac_f64_e32 v[2:3], v[18:19], v[26:27]
	v_mul_f64 v[16:17], v[12:13], v[22:23]
	v_div_scale_f64 v[18:19], s[14:15], s[12:13], s[12:13], v[10:11]
	v_fma_f64 v[12:13], -v[20:21], v[16:17], v[12:13]
	v_rcp_f64_e32 v[20:21], v[18:19]
	v_div_fmas_f64 v[12:13], v[12:13], v[22:23], v[16:17]
	v_div_fixup_f64 v[12:13], v[12:13], s[10:11], v[10:11]
	s_mov_b32 s10, 0
	v_fma_f64 v[22:23], -v[18:19], v[20:21], 1.0
	v_fmac_f64_e32 v[20:21], v[20:21], v[22:23]
	v_fma_f64 v[22:23], -v[18:19], v[20:21], 1.0
	v_fmac_f64_e32 v[20:21], v[20:21], v[22:23]
	v_div_scale_f64 v[22:23], vcc, v[10:11], s[12:13], v[10:11]
	v_mul_f64 v[26:27], v[22:23], v[20:21]
	v_fma_f64 v[18:19], -v[18:19], v[26:27], v[22:23]
	s_mov_b32 s11, 0x4066c000
	s_nop 0
	v_div_fmas_f64 v[18:19], v[18:19], v[20:21], v[26:27]
	v_div_fixup_f64 v[18:19], v[18:19], s[12:13], v[10:11]
	v_div_scale_f64 v[20:21], s[12:13], s[10:11], s[10:11], v[10:11]
	v_rcp_f64_e32 v[22:23], v[20:21]
	v_mul_f64 v[16:17], v[12:13], v[14:15]
	v_fmac_f64_e32 v[8:9], v[12:13], v[14:15]
	s_mov_b32 s12, 0
	v_fma_f64 v[12:13], -v[20:21], v[22:23], 1.0
	v_fmac_f64_e32 v[22:23], v[22:23], v[12:13]
	v_fma_f64 v[12:13], -v[20:21], v[22:23], 1.0
	v_fmac_f64_e32 v[22:23], v[22:23], v[12:13]
	v_div_scale_f64 v[12:13], vcc, v[10:11], s[10:11], v[10:11]
	s_mov_b32 s13, 0x406a4000
	v_mul_f64 v[26:27], v[18:19], v[24:25]
	v_fmac_f64_e32 v[2:3], v[18:19], v[24:25]
	v_mul_f64 v[14:15], v[12:13], v[22:23]
	v_div_scale_f64 v[18:19], s[14:15], s[12:13], s[12:13], v[10:11]
	v_fma_f64 v[12:13], -v[20:21], v[14:15], v[12:13]
	v_rcp_f64_e32 v[20:21], v[18:19]
	v_div_fmas_f64 v[12:13], v[12:13], v[22:23], v[14:15]
	v_div_fixup_f64 v[12:13], v[12:13], s[10:11], v[10:11]
	s_mov_b32 s10, 0
	v_fma_f64 v[22:23], -v[18:19], v[20:21], 1.0
	v_fmac_f64_e32 v[20:21], v[20:21], v[22:23]
	v_fma_f64 v[22:23], -v[18:19], v[20:21], 1.0
	v_fmac_f64_e32 v[20:21], v[20:21], v[22:23]
	v_div_scale_f64 v[22:23], vcc, v[10:11], s[12:13], v[10:11]
	v_mul_f64 v[24:25], v[22:23], v[20:21]
	v_fma_f64 v[18:19], -v[18:19], v[24:25], v[22:23]
	s_mov_b32 s11, 0x406e0000
	s_nop 0
	v_div_fmas_f64 v[18:19], v[18:19], v[20:21], v[24:25]
	v_div_fixup_f64 v[18:19], v[18:19], s[12:13], v[10:11]
	v_div_scale_f64 v[20:21], s[12:13], s[10:11], s[10:11], v[10:11]
	v_rcp_f64_e32 v[22:23], v[20:21]
	v_mul_f64 v[14:15], v[12:13], v[16:17]
	v_fmac_f64_e32 v[8:9], v[12:13], v[16:17]
	s_mov_b32 s12, 0
	v_fma_f64 v[12:13], -v[20:21], v[22:23], 1.0
	v_fmac_f64_e32 v[22:23], v[22:23], v[12:13]
	v_fma_f64 v[12:13], -v[20:21], v[22:23], 1.0
	v_fmac_f64_e32 v[22:23], v[22:23], v[12:13]
	v_div_scale_f64 v[12:13], vcc, v[10:11], s[10:11], v[10:11]
	s_mov_b32 s13, 0x40710000
	v_mul_f64 v[24:25], v[18:19], v[26:27]
	v_fmac_f64_e32 v[2:3], v[18:19], v[26:27]
	v_mul_f64 v[16:17], v[12:13], v[22:23]
	v_div_scale_f64 v[18:19], s[14:15], s[12:13], s[12:13], v[10:11]
	v_fma_f64 v[12:13], -v[20:21], v[16:17], v[12:13]
	v_rcp_f64_e32 v[20:21], v[18:19]
	v_div_fmas_f64 v[12:13], v[12:13], v[22:23], v[16:17]
	v_div_fixup_f64 v[12:13], v[12:13], s[10:11], v[10:11]
	s_mov_b32 s10, 0
	v_fma_f64 v[22:23], -v[18:19], v[20:21], 1.0
	v_fmac_f64_e32 v[20:21], v[20:21], v[22:23]
	v_fma_f64 v[22:23], -v[18:19], v[20:21], 1.0
	v_fmac_f64_e32 v[20:21], v[20:21], v[22:23]
	v_div_scale_f64 v[22:23], vcc, v[10:11], s[12:13], v[10:11]
	v_mul_f64 v[26:27], v[22:23], v[20:21]
	v_fma_f64 v[18:19], -v[18:19], v[26:27], v[22:23]
	s_mov_b32 s11, 0x40732000
	s_nop 0
	v_div_fmas_f64 v[18:19], v[18:19], v[20:21], v[26:27]
	v_div_fixup_f64 v[18:19], v[18:19], s[12:13], v[10:11]
	v_div_scale_f64 v[20:21], s[12:13], s[10:11], s[10:11], v[10:11]
	v_rcp_f64_e32 v[22:23], v[20:21]
	v_mul_f64 v[16:17], v[12:13], v[14:15]
	v_fmac_f64_e32 v[8:9], v[12:13], v[14:15]
	s_mov_b32 s12, 0
	v_fma_f64 v[12:13], -v[20:21], v[22:23], 1.0
	v_fmac_f64_e32 v[22:23], v[22:23], v[12:13]
	v_fma_f64 v[12:13], -v[20:21], v[22:23], 1.0
	v_fmac_f64_e32 v[22:23], v[22:23], v[12:13]
	v_div_scale_f64 v[12:13], vcc, v[10:11], s[10:11], v[10:11]
	s_mov_b32 s13, 0x40756000
	v_mul_f64 v[26:27], v[18:19], v[24:25]
	v_fmac_f64_e32 v[2:3], v[18:19], v[24:25]
	v_mul_f64 v[14:15], v[12:13], v[22:23]
	v_div_scale_f64 v[18:19], s[14:15], s[12:13], s[12:13], v[10:11]
	v_fma_f64 v[12:13], -v[20:21], v[14:15], v[12:13]
	v_rcp_f64_e32 v[20:21], v[18:19]
	v_div_fmas_f64 v[12:13], v[12:13], v[22:23], v[14:15]
	v_div_fixup_f64 v[12:13], v[12:13], s[10:11], v[10:11]
	s_mov_b32 s10, 0
	v_fma_f64 v[22:23], -v[18:19], v[20:21], 1.0
	v_fmac_f64_e32 v[20:21], v[20:21], v[22:23]
	v_fma_f64 v[22:23], -v[18:19], v[20:21], 1.0
	v_fmac_f64_e32 v[20:21], v[20:21], v[22:23]
	v_div_scale_f64 v[22:23], vcc, v[10:11], s[12:13], v[10:11]
	v_mul_f64 v[24:25], v[22:23], v[20:21]
	v_fma_f64 v[18:19], -v[18:19], v[24:25], v[22:23]
	s_mov_b32 s11, 0x4077c000
	s_nop 0
	v_div_fmas_f64 v[18:19], v[18:19], v[20:21], v[24:25]
	v_div_fixup_f64 v[18:19], v[18:19], s[12:13], v[10:11]
	v_div_scale_f64 v[20:21], s[12:13], s[10:11], s[10:11], v[10:11]
	v_rcp_f64_e32 v[22:23], v[20:21]
	v_mul_f64 v[14:15], v[12:13], v[16:17]
	v_fmac_f64_e32 v[8:9], v[12:13], v[16:17]
	s_mov_b32 s12, 0
	v_fma_f64 v[12:13], -v[20:21], v[22:23], 1.0
	v_fmac_f64_e32 v[22:23], v[22:23], v[12:13]
	v_fma_f64 v[12:13], -v[20:21], v[22:23], 1.0
	v_fmac_f64_e32 v[22:23], v[22:23], v[12:13]
	v_div_scale_f64 v[12:13], vcc, v[10:11], s[10:11], v[10:11]
	s_mov_b32 s13, 0x407a4000
	v_mul_f64 v[24:25], v[18:19], v[26:27]
	v_fmac_f64_e32 v[2:3], v[18:19], v[26:27]
	v_mul_f64 v[16:17], v[12:13], v[22:23]
	v_div_scale_f64 v[18:19], s[14:15], s[12:13], s[12:13], v[10:11]
	v_fma_f64 v[12:13], -v[20:21], v[16:17], v[12:13]
	v_rcp_f64_e32 v[20:21], v[18:19]
	v_div_fmas_f64 v[12:13], v[12:13], v[22:23], v[16:17]
	v_div_fixup_f64 v[12:13], v[12:13], s[10:11], v[10:11]
	s_mov_b32 s10, 0
	v_fma_f64 v[22:23], -v[18:19], v[20:21], 1.0
	v_fmac_f64_e32 v[20:21], v[20:21], v[22:23]
	v_fma_f64 v[22:23], -v[18:19], v[20:21], 1.0
	v_fmac_f64_e32 v[20:21], v[20:21], v[22:23]
	v_div_scale_f64 v[22:23], vcc, v[10:11], s[12:13], v[10:11]
	v_mul_f64 v[26:27], v[22:23], v[20:21]
	v_fma_f64 v[18:19], -v[18:19], v[26:27], v[22:23]
	s_mov_b32 s11, 0x407ce000
	s_nop 0
	v_div_fmas_f64 v[18:19], v[18:19], v[20:21], v[26:27]
	v_div_fixup_f64 v[18:19], v[18:19], s[12:13], v[10:11]
	v_div_scale_f64 v[20:21], s[12:13], s[10:11], s[10:11], v[10:11]
	v_rcp_f64_e32 v[22:23], v[20:21]
	v_mul_f64 v[16:17], v[12:13], v[14:15]
	v_fmac_f64_e32 v[8:9], v[12:13], v[14:15]
	s_mov_b32 s12, 0
	v_fma_f64 v[12:13], -v[20:21], v[22:23], 1.0
	v_fmac_f64_e32 v[22:23], v[22:23], v[12:13]
	v_fma_f64 v[12:13], -v[20:21], v[22:23], 1.0
	v_fmac_f64_e32 v[22:23], v[22:23], v[12:13]
	v_div_scale_f64 v[12:13], vcc, v[10:11], s[10:11], v[10:11]
	s_mov_b32 s13, 0x407fa000
	v_mul_f64 v[26:27], v[18:19], v[24:25]
	v_fmac_f64_e32 v[2:3], v[18:19], v[24:25]
	v_mul_f64 v[14:15], v[12:13], v[22:23]
	v_div_scale_f64 v[18:19], s[14:15], s[12:13], s[12:13], v[10:11]
	v_fma_f64 v[12:13], -v[20:21], v[14:15], v[12:13]
	v_rcp_f64_e32 v[20:21], v[18:19]
	v_div_fmas_f64 v[12:13], v[12:13], v[22:23], v[14:15]
	v_div_fixup_f64 v[12:13], v[12:13], s[10:11], v[10:11]
	v_fmac_f64_e32 v[8:9], v[12:13], v[16:17]
	v_fma_f64 v[14:15], -v[18:19], v[20:21], 1.0
	v_fmac_f64_e32 v[20:21], v[20:21], v[14:15]
	v_fma_f64 v[14:15], -v[18:19], v[20:21], 1.0
	v_fmac_f64_e32 v[20:21], v[20:21], v[14:15]
	v_div_scale_f64 v[14:15], vcc, v[10:11], s[12:13], v[10:11]
	v_mul_f64 v[22:23], v[14:15], v[20:21]
	v_fma_f64 v[14:15], -v[18:19], v[22:23], v[14:15]
	s_mov_b64 s[10:11], 0
	s_nop 0
	v_div_fmas_f64 v[14:15], v[14:15], v[20:21], v[22:23]
	v_div_fixup_f64 v[10:11], v[14:15], s[12:13], v[10:11]
	v_fmac_f64_e32 v[2:3], v[10:11], v[26:27]
	s_mov_b64 s[12:13], 0x7ff
	s_branch .LBB0_30
